# L0 out-proj context tiles moved from a sparse 2nd round into the L1 in-proj phase (WGs 224-255), dependency via device-scope counter
# speedup vs baseline: 1.0419x; 1.0419x over previous
_Z14fwd_megakernel4Args:
	s_load_dwordx4 s[88:91], s[0:1], 0xc0
	s_mov_b32 s58, s2
	s_mov_b32 s98, 0
	v_cmp_gt_u32_e32 vcc, 2, v0
	s_and_saveexec_b64 s[4:5], vcc
	v_lshl_add_u32 v1, v0, 2, 0
	v_add_u32_e32 v1, 0x23fc0, v1
	v_mov_b32_e32 v2, 0
	ds_write_b32 v1, v2
	s_or_b64 exec, exec, s[4:5]
	s_load_dwordx16 s[72:87], s[0:1], 0x0
	s_waitcnt lgkmcnt(0)
	s_barrier
	s_add_u32 s60, s88, 0xc67d000
	s_getreg_b32 s2, hwreg(HW_REG_XCC_ID, 0, 4)
	s_addc_u32 s61, s89, 0
	s_and_b32 s59, s2, 15
	v_cmp_eq_u32_e64 s[62:63], 0, v0
	s_and_saveexec_b64 s[4:5], s[62:63]
	s_cbranch_execz .LBB0_5
	s_mov_b64 s[6:7], exec
	v_mbcnt_lo_u32_b32 v1, s6, 0
	v_mbcnt_hi_u32_b32 v1, s7, v1
	v_cmp_eq_u32_e32 vcc, 0, v1
	s_and_b64 s[2:3], exec, vcc
	s_mov_b64 exec, s[2:3]
	s_cbranch_execz .LBB0_5
	s_lshl_b32 s2, s59, 8
	s_bcnt1_i32_b64 s3, s[6:7]
	v_mov_b32_e32 v1, s2
	v_mov_b32_e32 v2, s3
	global_atomic_add v1, v2, s[60:61] offset:1024

.LBB0_539:
	s_add_i32 s24, s24, 1
	s_lshl_b32 s6, s24, 8
	v_readlane_b32 s7, v251, 48
	s_add_i32 s6, s6, s7
	s_cmpk_lt_i32 s6, 0x100
	s_cselect_b64 s[56:57], -1, 0
	s_ashr_i32 s6, s6, 2
	s_and_b32 s6, s6, -8
	v_readlane_b32 s7, v250, 11
	s_mov_b32 s3, s10
	s_mov_b32 s60, s10
	s_or_b32 s10, s6, s7
	s_and_b64 s[6:7], s[56:57], exec
	s_cselect_b32 s6, s10, s3
	s_ashr_i32 s7, s6, 31
	v_readlane_b32 s80, v251, 20
	s_lshl_b64 s[6:7], s[6:7], 19
	v_readlane_b32 s94, v251, 34
	s_mov_b64 s[34:35], s[12:13]
	v_readlane_b32 s95, v251, 35
	s_add_u32 s12, s94, s6
	s_addc_u32 s13, s95, s7
	s_and_b64 s[6:7], s[56:57], exec
	s_cselect_b32 s3, s13, s35
	s_cselect_b32 s6, s12, s34
	s_add_u32 s62, s34, 0x40080
	s_addc_u32 s63, s35, 0
	s_mov_b32 s7, -2
	s_mov_b64 s[66:67], s[48:49]
	v_mov_b32_e32 v2, v171
	v_mov_b32_e32 v3, v171
	v_mov_b32_e32 v4, v171
	v_mov_b32_e32 v5, v171
	v_mov_b32_e32 v6, v171
	v_mov_b32_e32 v7, v171
	v_mov_b32_e32 v8, v171
	v_mov_b32_e32 v9, v171
	v_mov_b32_e32 v18, v171
	v_mov_b32_e32 v19, v171
	v_mov_b32_e32 v20, v171
	v_mov_b32_e32 v21, v171
	v_mov_b32_e32 v22, v171
	v_mov_b32_e32 v23, v171
	v_mov_b32_e32 v24, v171
	v_mov_b32_e32 v25, v171
	v_mov_b32_e32 v34, v171
	v_mov_b32_e32 v35, v171
	v_mov_b32_e32 v36, v171
	v_mov_b32_e32 v37, v171
	v_mov_b32_e32 v38, v171
	v_mov_b32_e32 v39, v171
	v_mov_b32_e32 v40, v171
	v_mov_b32_e32 v41, v171
	v_mov_b32_e32 v50, v171
	v_mov_b32_e32 v51, v171
	v_mov_b32_e32 v52, v171
	v_mov_b32_e32 v53, v171
	v_mov_b32_e32 v54, v171
	v_mov_b32_e32 v55, v171
	v_mov_b32_e32 v56, v171
	v_mov_b32_e32 v57, v171
	v_mov_b32_e32 v10, v171
	v_mov_b32_e32 v11, v171
	v_mov_b32_e32 v12, v171
	v_mov_b32_e32 v13, v171
	v_mov_b32_e32 v14, v171
	v_mov_b32_e32 v15, v171
	v_mov_b32_e32 v16, v171
	v_mov_b32_e32 v17, v171
	v_mov_b32_e32 v26, v171
	v_mov_b32_e32 v27, v171
	v_mov_b32_e32 v28, v171
	v_mov_b32_e32 v29, v171
	v_mov_b32_e32 v30, v171
	v_mov_b32_e32 v31, v171
	v_mov_b32_e32 v32, v171
	v_mov_b32_e32 v33, v171
	v_mov_b32_e32 v42, v171
	v_mov_b32_e32 v43, v171
	v_mov_b32_e32 v44, v171
	v_mov_b32_e32 v45, v171
	v_mov_b32_e32 v46, v171
	v_mov_b32_e32 v47, v171
	v_mov_b32_e32 v48, v171
	v_mov_b32_e32 v49, v171
	v_mov_b32_e32 v58, v171
	v_mov_b32_e32 v59, v171
	v_mov_b32_e32 v60, v171
	v_mov_b32_e32 v61, v171
	v_mov_b32_e32 v62, v171
	v_mov_b32_e32 v63, v171
	v_mov_b32_e32 v64, v171
	v_mov_b32_e32 v65, v171
	v_mov_b32_e32 v66, v171
	v_mov_b32_e32 v67, v171
	v_mov_b32_e32 v68, v171
	v_mov_b32_e32 v69, v171
	v_mov_b32_e32 v70, v171
	v_mov_b32_e32 v71, v171
	v_mov_b32_e32 v72, v171
	v_mov_b32_e32 v73, v171
	v_mov_b32_e32 v82, v171
	v_mov_b32_e32 v83, v171
	v_mov_b32_e32 v84, v171
	v_mov_b32_e32 v85, v171
	v_mov_b32_e32 v86, v171
	v_mov_b32_e32 v87, v171
	v_mov_b32_e32 v88, v171
	v_mov_b32_e32 v89, v171
	v_mov_b32_e32 v98, v171
	v_mov_b32_e32 v99, v171
	v_mov_b32_e32 v100, v171
	v_mov_b32_e32 v101, v171
	v_mov_b32_e32 v102, v171
	v_mov_b32_e32 v103, v171
	v_mov_b32_e32 v104, v171
	v_mov_b32_e32 v105, v171
	v_mov_b32_e32 v122, v171
	v_mov_b32_e32 v123, v171
	v_mov_b32_e32 v124, v171
	v_mov_b32_e32 v125, v171
	v_mov_b32_e32 v134, v171
	v_mov_b32_e32 v135, v171
	v_mov_b32_e32 v136, v171
	v_mov_b32_e32 v137, v171
	v_mov_b32_e32 v74, v171
	v_mov_b32_e32 v75, v171
	v_mov_b32_e32 v76, v171
	v_mov_b32_e32 v77, v171
	v_mov_b32_e32 v78, v171
	v_mov_b32_e32 v79, v171
	v_mov_b32_e32 v80, v171
	v_mov_b32_e32 v81, v171
	v_mov_b32_e32 v90, v171
	v_mov_b32_e32 v91, v171
	v_mov_b32_e32 v92, v171
	v_mov_b32_e32 v93, v171
	v_mov_b32_e32 v94, v171
	v_mov_b32_e32 v95, v171
	v_mov_b32_e32 v96, v171
	v_mov_b32_e32 v97, v171
	v_mov_b32_e32 v106, v171
	v_mov_b32_e32 v107, v171
	v_mov_b32_e32 v108, v171
	v_mov_b32_e32 v109, v171
	v_mov_b32_e32 v110, v171
	v_mov_b32_e32 v111, v171
	v_mov_b32_e32 v112, v171
	v_mov_b32_e32 v113, v171
	v_mov_b32_e32 v142, v171
	v_mov_b32_e32 v143, v171
	v_mov_b32_e32 v144, v171
	v_mov_b32_e32 v145, v171
	v_mov_b32_e32 v130, v171
	v_mov_b32_e32 v131, v171
	v_mov_b32_e32 v132, v171
	v_mov_b32_e32 v133, v171
	v_readlane_b32 s81, v251, 21
	v_readlane_b32 s82, v251, 22
	v_readlane_b32 s83, v251, 23
	v_readlane_b32 s84, v251, 24
	v_readlane_b32 s85, v251, 25
	v_readlane_b32 s86, v251, 26
	v_readlane_b32 s87, v251, 27
	v_readlane_b32 s88, v251, 28
	v_readlane_b32 s89, v251, 29
	v_readlane_b32 s90, v251, 30
	v_readlane_b32 s91, v251, 31
	v_readlane_b32 s92, v251, 32
	v_readlane_b32 s93, v251, 33

.LBB0_581:
	s_cmp_eq_u32 s98, 1
	s_cbranch_scc1 .Lp4b_done
	s_cmp_gt_i32 s91, 5
	s_cselect_b64 s[0:1], -1, 0
	s_and_b64 s[2:3], s[92:93], s[0:1]
	s_andn2_b64 vcc, exec, s[2:3]
	s_cbranch_vccnz .LBB0_635
	s_waitcnt vmcnt(0)
	s_waitcnt vmcnt(0)
	s_barrier
	s_and_saveexec_b64 s[4:5], s[62:63]
	s_cbranch_execz .LBB0_634
	s_add_i32 s2, 0, 0x23fc0
	v_mov_b32_e32 v2, s2
	s_waitcnt vmcnt(0) expcnt(0) lgkmcnt(0)
	ds_read_b32 v4, v2
	s_add_i32 s2, 0, 0x23fc4
	v_mov_b32_e32 v2, s2
	ds_read_b32 v2, v2
	s_waitcnt lgkmcnt(1)
	v_cmp_ne_u32_e32 vcc, 0, v4
	s_cbranch_vccnz .LBB0_598
	v_readlane_b32 s6, v251, 0
	v_readlane_b32 s7, v251, 1
	s_load_dwordx2 s[2:3], s[6:7], 0x4
	s_add_u32 s6, s88, 0xc67d200
	s_addc_u32 s7, s89, 0
	s_add_u32 s8, s88, 0xc67d400
	s_addc_u32 s9, s89, 0
	s_add_u32 s10, s88, 0xc67d500
	s_addc_u32 s11, s89, 0
	s_add_u32 s12, s88, 0xc67d600
	s_addc_u32 s13, s89, 0
	s_add_u32 s14, s88, 0xc67d700
	s_addc_u32 s15, s89, 0
	s_add_u32 s16, s88, 0xc67d800
	s_addc_u32 s17, s89, 0
	s_add_u32 s18, s88, 0xc67d900
	s_addc_u32 s19, s89, 0
	s_add_u32 s20, s88, 0xc67da00
	s_addc_u32 s21, s89, 0
	s_add_u32 s22, s88, 0xc67db00
	s_addc_u32 s23, s89, 0
	s_add_u32 s24, s88, 0xc67dc00
	s_addc_u32 s25, s89, 0
	s_add_u32 s28, s88, 0xc67dd00
	s_addc_u32 s29, s89, 0
	s_add_u32 s30, s88, 0xc67de00
	s_addc_u32 s31, s89, 0
	s_add_u32 s36, s88, 0xc67df00
	s_addc_u32 s37, s89, 0
	s_add_u32 s38, s88, 0xc67e000
	s_addc_u32 s39, s89, 0
	s_add_u32 s40, s88, 0xc67e100
	s_addc_u32 s41, s89, 0
	s_add_u32 s42, s88, 0xc67e200
	s_addc_u32 s43, s89, 0
	s_waitcnt lgkmcnt(0)
	s_mul_i32 s2, s2, s69
	s_add_u32 s44, s88, 0xc67e300
	s_mul_i32 s2, s2, s3
	s_addc_u32 s45, s89, 0
	s_mov_b32 s3, 1
	v_mov_b32_e32 v18, 0
	s_branch .LBB0_586

.LBB0_695:
	s_cmpk_lt_i32 s58, 0xe0
	s_cbranch_scc1 .Lp6_main
	s_cmp_lg_u32 s98, 0
	s_cbranch_scc1 .Lp6_main
	s_mov_b32 s98, 1
	s_add_u32 s2, s88, 0x480000
	s_addc_u32 s3, s89, 0
	v_writelane_b32 v251, s2, 36
	v_writelane_b32 v251, s3, 37
	s_add_i32 s58, s58, 32
	s_mov_b64 s[0:1], -1
	s_branch .LBB0_479
.Lp4b_done:
	s_mov_b32 s98, 2
	s_and_saveexec_b64 s[4:5], s[62:63]
	s_cbranch_execz .Lp4b_rel_done
	buffer_wbl2 sc1
	s_waitcnt vmcnt(0)
	v_mov_b32_e32 v2, 0x7000
	v_mov_b32_e32 v3, 1
	global_atomic_add v2, v3, s[60:61]
	s_waitcnt vmcnt(0)
.Lp4b_rel_done:
	s_or_b64 exec, exec, s[4:5]
	s_cmp_gt_i32 s91, 5
	s_cselect_b64 s[0:1], -1, 0
	s_branch .LBB0_635

.LBB0_705:
	s_add_i32 s43, s43, 1
	s_mul_i32 s0, s43, s44
	s_mul_hi_u32 s1, s43, s69
	s_add_i32 s1, s1, s0
	s_mul_i32 s0, s43, s69
	s_add_u32 s22, s0, s58
	s_addc_u32 s23, s1, s2
	s_cmp_lt_u32 s43, 2
	s_cbranch_scc1 .Lp6_sched_done
	s_cmpk_lt_u32 s58, 0xe0
	s_cbranch_scc1 .Lp6_sched_mid
	s_movk_i32 s22, 0x378
	s_mov_b32 s23, 0
	s_branch .Lp6_sched_done
.Lp6_sched_mid:
	s_cmp_lg_u32 s43, 3
	s_cbranch_scc1 .Lp6_sched_done
	s_cmpk_lt_u32 s58, 0x78
	s_cbranch_scc1 .Lp6_sched_done
	s_cmpk_gt_u32 s58, 0x97
	s_cbranch_scc1 .Lp6_sched_done
	s_add_i32 s22, s58, 0x268
	s_mov_b32 s23, 0
.Lp6_sched_done:
	v_cmp_gt_i64_e32 vcc, s[22:23], v[146:147]
	v_cmp_lt_i64_e64 s[0:1], s[22:23], v[144:145]
	s_cbranch_vccnz .LBB0_710
	v_cmp_lt_i64_e32 vcc, s[22:23], v[148:149]
	s_mov_b64 s[28:29], -1
	s_cbranch_vccnz .LBB0_708
	s_mov_b32 s100, 0
.Lp6_ctx_wait:
	v_mov_b32_e32 v2, 0x7000
	global_load_dword v2, v2, s[60:61] sc1
	s_waitcnt vmcnt(0)
	v_readfirstlane_b32 s99, v2
	s_nop 3
	s_cmp_ge_u32 s99, 32
	s_cbranch_scc1 .Lp6_ctx_ready
	s_add_i32 s100, s100, 1
	s_cmp_gt_u32 s100, 0x40000
	s_cbranch_scc1 .Lp6_ctx_ready
	s_sleep 2
	s_branch .Lp6_ctx_wait
.Lp6_ctx_ready:
	buffer_inv sc1
	s_waitcnt vmcnt(0)
	s_add_i32 s19, s22, 0xfffffcc0
	s_mul_hi_i32 s18, s19, 0x92492493
	s_add_i32 s18, s18, s19
	s_lshr_b32 s20, s18, 31
	s_ashr_i32 s18, s18, 2
	s_add_i32 s20, s18, s20
	s_add_i32 s18, s20, 64
	s_mul_i32 s20, s20, 7
	s_sub_i32 s19, s19, s20
	s_add_i32 s20, s19, 2
	s_cmp_lt_i32 s19, 6
	s_cselect_b32 s20, s20, 12
	s_mov_b64 s[28:29], 0

	.amdhsa_kernel _Z14fwd_megakernel4Args
		.amdhsa_group_segment_fixed_size 0
		.amdhsa_private_segment_fixed_size 0
		.amdhsa_kernarg_size 464
		.amdhsa_user_sgpr_count 2
		.amdhsa_user_sgpr_dispatch_ptr 0
		.amdhsa_user_sgpr_queue_ptr 0
		.amdhsa_user_sgpr_kernarg_segment_ptr 1
		.amdhsa_user_sgpr_dispatch_id 0
		.amdhsa_user_sgpr_kernarg_preload_length 0
		.amdhsa_user_sgpr_kernarg_preload_offset 0
		.amdhsa_user_sgpr_private_segment_size 0
		.amdhsa_uses_dynamic_stack 0
		.amdhsa_enable_private_segment 0
		.amdhsa_system_sgpr_workgroup_id_x 1
		.amdhsa_system_sgpr_workgroup_id_y 0
		.amdhsa_system_sgpr_workgroup_id_z 0
		.amdhsa_system_sgpr_workgroup_info 0
		.amdhsa_system_vgpr_workitem_id 0
		.amdhsa_next_free_vgpr 252
		.amdhsa_next_free_sgpr 102
		.amdhsa_accum_offset 252
		.amdhsa_reserve_vcc 1
		.amdhsa_float_round_mode_32 0
		.amdhsa_float_round_mode_16_64 0
		.amdhsa_float_denorm_mode_32 3
		.amdhsa_float_denorm_mode_16_64 3
		.amdhsa_dx10_clamp 1
		.amdhsa_ieee_mode 1
		.amdhsa_fp16_overflow 0
		.amdhsa_tg_split 0
		.amdhsa_exception_fp_ieee_invalid_op 0
		.amdhsa_exception_fp_denorm_src 0
		.amdhsa_exception_fp_ieee_div_zero 0
		.amdhsa_exception_fp_ieee_overflow 0
		.amdhsa_exception_fp_ieee_underflow 0
		.amdhsa_exception_fp_ieee_inexact 0
		.amdhsa_exception_int_div_zero 0
	.end_amdhsa_kernel

amdhsa.kernels:
  - .agpr_count:     0
    .args:
      - .offset:         0
        .size:           208
        .value_kind:     by_value
      - .offset:         208
        .size:           4
        .value_kind:     hidden_block_count_x
      - .offset:         212
        .size:           4
        .value_kind:     hidden_block_count_y
      - .offset:         216
        .size:           4
        .value_kind:     hidden_block_count_z
      - .offset:         220
        .size:           2
        .value_kind:     hidden_group_size_x
      - .offset:         222
        .size:           2
        .value_kind:     hidden_group_size_y
      - .offset:         224
        .size:           2
        .value_kind:     hidden_group_size_z
      - .offset:         226
        .size:           2
        .value_kind:     hidden_remainder_x
      - .offset:         228
        .size:           2
        .value_kind:     hidden_remainder_y
      - .offset:         230
        .size:           2
        .value_kind:     hidden_remainder_z
      - .offset:         248
        .size:           8
        .value_kind:     hidden_global_offset_x
      - .offset:         256
        .size:           8
        .value_kind:     hidden_global_offset_y
      - .offset:         264
        .size:           8
        .value_kind:     hidden_global_offset_z
      - .offset:         272
        .size:           2
        .value_kind:     hidden_grid_dims
      - .offset:         328
        .size:           4
        .value_kind:     hidden_dynamic_lds_size
    .group_segment_fixed_size: 0
    .kernarg_segment_align: 8
    .kernarg_segment_size: 464
    .language:       OpenCL C
    .language_version:
      - 2
      - 0
    .max_flat_workgroup_size: 512
    .name:           _Z14fwd_megakernel4Args
    .private_segment_fixed_size: 0
    .sgpr_count:     108
    .sgpr_spill_count: 97
    .symbol:         _Z14fwd_megakernel4Args.kd
    .uniform_work_group_size: 1
    .uses_dynamic_stack: false
    .vgpr_count:     252
    .vgpr_spill_count: 0
    .wavefront_size: 64
